# first phase (weight transposition, rmsnorm rows, log-forget) stores write-through; the grid barrier after it no longer does an L2 write-back
# baseline (speedup 1.0000x reference)
; DI unsigned pk2(float a, float b) { f32x2 v = {a, b}; bf16x2v r = __builtin_convertvector(v, bf16x2v); return __builtin_bit_cast(unsigned, r); }
; DI void phase0(const Params& p, char* smem) {
;     ...
;     for (int u = blockIdx.x; u < 1280; u += gridDim.x) {
;         const float* src; int ld; bf16_t* dst;
;         if (u < 1024) { const int kt = u >> 6, nt = u & 63; src = p.w_in + (size_t)(kt * 64) * INW + nt * 64; ld = INW; dst = p.wtin + (size_t)(nt * 64) * DM + kt * 64; }
;         else { const int v = u - 1024, kt = v >> 4, nt = v & 15; src = p.w_out + (size_t)(kt * 64) * DM + nt * 64; ld = DM; dst = p.wtout + (size_t)(nt * 64) * DM + kt * 64; }
; #pragma unroll
;         for (int i = 0; i < 2; ++i) {
;             const int r = (tid >> 4) + 32 * i, c = (tid & 15) * 4;
;             const f32x4 v = *(const f32x4*)(src + (size_t)r * ld + c);
;             tile[r * 65 + c] = v[0]; tile[r * 65 + c + 1] = v[1]; tile[r * 65 + c + 2] = v[2]; tile[r * 65 + c + 3] = v[3];
;         }
;         __syncthreads();
;         {
;             const int n = (tid >> 3), kc = (tid & 7) * 8;
;             u32x4 w;
;             w[0] = pk2(tile[(kc + 0) * 65 + n], tile[(kc + 1) * 65 + n]);
;             w[1] = pk2(tile[(kc + 2) * 65 + n], tile[(kc + 3) * 65 + n]);
;             w[2] = pk2(tile[(kc + 4) * 65 + n], tile[(kc + 5) * 65 + n]);
;             w[3] = pk2(tile[(kc + 6) * 65 + n], tile[(kc + 7) * 65 + n]);
;             *(u32x4*)(dst + (size_t)n * DM + kc) = w;
;         }
;         __syncthreads();
.LBB0_8:
	s_and_b32 s4, s15, s4
	s_lshl_b32 s13, s4, 2
	s_add_u32 s10, s10, s13
	s_addc_u32 s11, s11, 0
	v_lshl_add_u64 v[18:19], s[10:11], 0, v[4:5]
	v_mad_i64_i32 v[14:15], s[10:11], s12, v2, 0
	v_lshl_add_u64 v[14:15], v[14:15], 2, v[18:19]
	global_load_dwordx4 v[14:17], v[14:15], off
	v_mad_i64_i32 v[20:21], s[10:11], s12, v8, 0
	v_lshl_add_u64 v[18:19], v[20:21], 2, v[18:19]
	global_load_dwordx4 v[18:21], v[18:19], off
	s_lshl_b32 s4, s4, 11
	s_add_u32 s4, s8, s4
	s_addc_u32 s8, s9, 0
	s_lshl_b64 s[6:7], s[6:7], 1
	s_add_u32 s6, s4, s6
	s_addc_u32 s7, s8, s7
	s_add_i32 s19, s19, s14
	s_add_i32 s15, s15, s16
	s_add_i32 s17, s17, s18
	v_lshl_add_u64 v[22:23], s[6:7], 0, v[6:7]
	s_cmpk_gt_i32 s19, 0x4ff
	v_lshl_add_u64 v[22:23], v[22:23], 0, v[10:11]
	s_waitcnt vmcnt(1)
	ds_write2_b32 v3, v14, v15 offset1:1
	ds_write2_b32 v3, v16, v17 offset0:2 offset1:3
	s_waitcnt vmcnt(0)
	ds_write2_b32 v9, v18, v19 offset1:1
	ds_write2_b32 v12, v20, v21 offset1:1
	s_waitcnt lgkmcnt(0)
	s_barrier
	ds_read2_b32 v[14:15], v1 offset1:65
	ds_read2_b32 v[16:17], v1 offset0:130 offset1:195
	ds_read2_b32 v[18:19], v13 offset0:4 offset1:69
	ds_read2_b32 v[20:21], v13 offset0:134 offset1:199
	s_waitcnt lgkmcnt(3)
	v_cvt_pk_bf16_f32 v14, v14, v15
	s_waitcnt lgkmcnt(2)
	v_cvt_pk_bf16_f32 v15, v16, v17
	s_waitcnt lgkmcnt(1)
	v_cvt_pk_bf16_f32 v16, v18, v19
	s_waitcnt lgkmcnt(0)
	v_cvt_pk_bf16_f32 v17, v20, v21
	global_store_dwordx4 v[22:23], v[14:17], off sc0 sc1
	s_barrier
	s_cbranch_scc1 .LBB0_13

; DI unsigned pk2(float a, float b) { f32x2 v = {a, b}; bf16x2v r = __builtin_convertvector(v, bf16x2v); return __builtin_bit_cast(unsigned, r); }
; DI void phase0(const Params& p, char* smem) {
;     ...
; #pragma unroll
;         for (int i = 0; i < 2; ++i) {
;             const int r = (tid >> 4) + 32 * i, c = (tid & 15) * 4;
;             const f32x4 v = *(const f32x4*)(src + (size_t)r * ld + c);
;             tile[r * 65 + c] = v[0]; tile[r * 65 + c + 1] = v[1]; tile[r * 65 + c + 2] = v[2]; tile[r * 65 + c + 3] = v[3];
;         }
;         __syncthreads();
;         {
;             const int n = (tid >> 3), kc = (tid & 7) * 8;
;             u32x4 w;
;             w[0] = pk2(tile[(kc + 0) * 65 + n], tile[(kc + 1) * 65 + n]);
;             w[1] = pk2(tile[(kc + 2) * 65 + n], tile[(kc + 3) * 65 + n]);
;             w[2] = pk2(tile[(kc + 4) * 65 + n], tile[(kc + 5) * 65 + n]);
;             w[3] = pk2(tile[(kc + 6) * 65 + n], tile[(kc + 7) * 65 + n]);
;             *(u32x4*)(dst + (size_t)n * DM + kc) = w;
;         }
;         __syncthreads();
.Lp0t_issued:
	s_waitcnt vmcnt(0)
	s_bitcmp1_b32 s20, 0
	s_cbranch_scc0 .Lp0t_done
	ds_write2_b32 v3, v24, v25 offset1:1
	ds_write2_b32 v3, v26, v27 offset0:2 offset1:3
	ds_write2_b32 v9, v28, v29 offset1:1
	ds_write2_b32 v12, v30, v31 offset1:1
	s_waitcnt lgkmcnt(0)
	s_barrier
	ds_read2_b32 v[14:15], v1 offset1:65
	ds_read2_b32 v[16:17], v1 offset0:130 offset1:195
	ds_read2_b32 v[18:19], v13 offset0:4 offset1:69
	ds_read2_b32 v[20:21], v13 offset0:134 offset1:199
	s_waitcnt lgkmcnt(3)
	v_cvt_pk_bf16_f32 v14, v14, v15
	s_waitcnt lgkmcnt(2)
	v_cvt_pk_bf16_f32 v15, v16, v17
	s_waitcnt lgkmcnt(1)
	v_cvt_pk_bf16_f32 v16, v18, v19
	s_waitcnt lgkmcnt(0)
	v_cvt_pk_bf16_f32 v17, v20, v21
	global_store_dwordx4 v[68:69], v[14:17], off sc0 sc1
	s_barrier
	s_bitcmp1_b32 s20, 1
	s_cbranch_scc0 .Lp0t_done
	ds_write2_b32 v3, v32, v33 offset1:1
	ds_write2_b32 v3, v34, v35 offset0:2 offset1:3
	ds_write2_b32 v9, v36, v37 offset1:1
	ds_write2_b32 v12, v38, v39 offset1:1
	s_waitcnt lgkmcnt(0)
	s_barrier
	ds_read2_b32 v[14:15], v1 offset1:65
	ds_read2_b32 v[16:17], v1 offset0:130 offset1:195
	ds_read2_b32 v[18:19], v13 offset0:4 offset1:69
	ds_read2_b32 v[20:21], v13 offset0:134 offset1:199
	s_waitcnt lgkmcnt(3)
	v_cvt_pk_bf16_f32 v14, v14, v15
	s_waitcnt lgkmcnt(2)
	v_cvt_pk_bf16_f32 v15, v16, v17
	s_waitcnt lgkmcnt(1)
	v_cvt_pk_bf16_f32 v16, v18, v19
	s_waitcnt lgkmcnt(0)
	v_cvt_pk_bf16_f32 v17, v20, v21
	global_store_dwordx4 v[70:71], v[14:17], off sc0 sc1
	s_barrier
	s_bitcmp1_b32 s20, 2
	s_cbranch_scc0 .Lp0t_done
	ds_write2_b32 v3, v40, v41 offset1:1
	ds_write2_b32 v3, v42, v43 offset0:2 offset1:3
	ds_write2_b32 v9, v44, v45 offset1:1
	ds_write2_b32 v12, v46, v47 offset1:1
	s_waitcnt lgkmcnt(0)
	s_barrier
	ds_read2_b32 v[14:15], v1 offset1:65
	ds_read2_b32 v[16:17], v1 offset0:130 offset1:195
	ds_read2_b32 v[18:19], v13 offset0:4 offset1:69
	ds_read2_b32 v[20:21], v13 offset0:134 offset1:199
	s_waitcnt lgkmcnt(3)
	v_cvt_pk_bf16_f32 v14, v14, v15
	s_waitcnt lgkmcnt(2)
	v_cvt_pk_bf16_f32 v15, v16, v17
	s_waitcnt lgkmcnt(1)
	v_cvt_pk_bf16_f32 v16, v18, v19
	s_waitcnt lgkmcnt(0)
	v_cvt_pk_bf16_f32 v17, v20, v21
	global_store_dwordx4 v[72:73], v[14:17], off sc0 sc1
	s_barrier
	s_bitcmp1_b32 s20, 3
	s_cbranch_scc0 .Lp0t_done
	ds_write2_b32 v3, v52, v53 offset1:1
	ds_write2_b32 v3, v54, v55 offset0:2 offset1:3
	ds_write2_b32 v9, v56, v57 offset1:1
	ds_write2_b32 v12, v58, v59 offset1:1
	s_waitcnt lgkmcnt(0)
	s_barrier
	ds_read2_b32 v[14:15], v1 offset1:65
	ds_read2_b32 v[16:17], v1 offset0:130 offset1:195
	ds_read2_b32 v[18:19], v13 offset0:4 offset1:69
	ds_read2_b32 v[20:21], v13 offset0:134 offset1:199
	s_waitcnt lgkmcnt(3)
	v_cvt_pk_bf16_f32 v14, v14, v15
	s_waitcnt lgkmcnt(2)
	v_cvt_pk_bf16_f32 v15, v16, v17
	s_waitcnt lgkmcnt(1)
	v_cvt_pk_bf16_f32 v16, v18, v19
	s_waitcnt lgkmcnt(0)
	v_cvt_pk_bf16_f32 v17, v20, v21
	global_store_dwordx4 v[74:75], v[14:17], off sc0 sc1
	s_barrier
	s_bitcmp1_b32 s20, 4
	s_cbranch_scc0 .Lp0t_done
	ds_write2_b32 v3, v60, v61 offset1:1
	ds_write2_b32 v3, v62, v63 offset0:2 offset1:3
	ds_write2_b32 v9, v64, v65 offset1:1
	ds_write2_b32 v12, v66, v67 offset1:1
	s_waitcnt lgkmcnt(0)
	s_barrier
	ds_read2_b32 v[14:15], v1 offset1:65
	ds_read2_b32 v[16:17], v1 offset0:130 offset1:195
	ds_read2_b32 v[18:19], v13 offset0:4 offset1:69
	ds_read2_b32 v[20:21], v13 offset0:134 offset1:199
	s_waitcnt lgkmcnt(3)
	v_cvt_pk_bf16_f32 v14, v14, v15
	s_waitcnt lgkmcnt(2)
	v_cvt_pk_bf16_f32 v15, v16, v17
	s_waitcnt lgkmcnt(1)
	v_cvt_pk_bf16_f32 v16, v18, v19
	s_waitcnt lgkmcnt(0)
	v_cvt_pk_bf16_f32 v17, v20, v21
	global_store_dwordx4 v[76:77], v[14:17], off sc0 sc1
	s_barrier

; #define LDS_AS __attribute__((address_space(3)))
; DI void phase0(const Params& p, char* smem) {
;     ...
;         float ss = 0.f;
; #pragma unroll
;         for (int i = 0; i < 4; ++i) ss += v[i][0] * v[i][0] + v[i][1] * v[i][1] + v[i][2] * v[i][2] + v[i][3] * v[i][3];
;         float fa[8];
; #pragma unroll
;         for (int j = 0; j < 8; ++j) fa[j] = 0.f;
;         f32x4 xg[4];
; #pragma unroll
;         for (int i = 0; i < 4; ++i) {
;             const int k = i * 256 + lane * 4;
;             xg[i] = v[i] * gq[i];
; #pragma unroll
;             for (int j = 0; j < 8; ++j) { const f32x4 w = *(LDS_AS const f32x4*)(wfl + (j * 1024 + k) * 4); fa[j] += xg[i][0] * w[0] + xg[i][1] * w[1] + xg[i][2] * w[2] + xg[i][3] * w[3]; }
;         }
.LBB0_52:
	s_or_b64 exec, exec, s[16:17]
	v_mov_b32_e32 v20, s77
	v_cmp_eq_u64_e32 vcc, 0, v[18:19]
	v_ashrrev_i32_e32 v65, 31, v64
	v_lshlrev_b64 v[64:65], 11, v[64:65]
	v_cndmask_b32_e32 v19, v19, v20, vcc
	v_mov_b32_e32 v20, s76
	v_cndmask_b32_e32 v18, v18, v20, vcc
	v_lshl_add_u64 v[30:31], v[18:19], 0, v[54:55]
	global_load_dwordx4 v[18:21], v[30:31], off
	global_load_dwordx4 v[22:25], v[30:31], off offset:1024
	global_load_dwordx4 v[26:29], v[30:31], off offset:2048
	s_nop 0
	global_load_dwordx4 v[30:33], v[30:31], off offset:3072
	v_lshl_add_u64 v[64:65], s[66:67], 0, v[64:65]
	v_cmp_ne_u64_e32 vcc, 0, v[66:67]
	v_lshlrev_b32_e32 v66, 1, v70
	s_and_saveexec_b64 s[16:17], vcc
	s_xor_b64 s[28:29], exec, s[16:17]
	s_cbranch_execz .LBB0_56
	s_waitcnt vmcnt(6)
	v_mov_b32_e32 v78, v39
	v_mov_b32_e32 v79, v35
	v_mov_b32_e32 v68, v38
	v_mov_b32_e32 v69, v34
	v_pk_mul_f32 v[78:79], v[78:79], v[78:79]
	v_mov_b32_e32 v80, v40
	v_mov_b32_e32 v81, v36
	v_pk_fma_f32 v[68:69], v[68:69], v[68:69], v[78:79]
	s_waitcnt vmcnt(4)
	v_mul_f32_e32 v53, v47, v47
	v_pk_fma_f32 v[68:69], v[80:81], v[80:81], v[68:69]
	ds_read_b128 v[78:81], v71
	v_mul_f32_e32 v57, v43, v43
	v_fmac_f32_e32 v57, v42, v42
	v_fmac_f32_e32 v53, v46, v46
	v_fmac_f32_e32 v57, v44, v44
	v_fmac_f32_e32 v53, v48, v48
	ds_read_b128 v[86:89], v71 offset:4096
	v_fmac_f32_e32 v57, v45, v45
	v_mov_b32_e32 v82, v41
	v_mov_b32_e32 v83, v37
	v_fmac_f32_e32 v53, v49, v49
	v_pk_mul_f32 v[46:47], v[2:3], v[46:47]
	v_pk_fma_f32 v[68:69], v[82:83], v[82:83], v[68:69]
	v_add_f32_e32 v53, v53, v57
	ds_read_b128 v[82:85], v71 offset:1024
	s_waitcnt lgkmcnt(2)
	v_mul_f32_e32 v57, v47, v79
	v_pk_mul_f32 v[48:49], v[4:5], v[48:49]
	v_fmac_f32_e32 v57, v46, v78
	ds_read_b128 v[90:93], v71 offset:8192
	v_fmac_f32_e32 v57, v48, v80
	v_fmac_f32_e32 v57, v49, v81
	ds_read_b128 v[78:81], v71 offset:5120
	s_waitcnt lgkmcnt(3)
	v_mul_f32_e32 v59, v47, v87
	v_fmac_f32_e32 v59, v46, v86
	ds_read_b128 v[94:97], v71 offset:12288
	v_fmac_f32_e32 v59, v48, v88
	v_fmac_f32_e32 v59, v49, v89
	ds_read_b128 v[86:89], v71 offset:9216
	s_waitcnt lgkmcnt(3)
	v_mul_f32_e32 v67, v47, v91
	v_fmac_f32_e32 v67, v46, v90
	ds_read_b128 v[98:101], v71 offset:16384
	v_fmac_f32_e32 v67, v48, v92
	v_add_f32_e32 v53, v53, v68
	v_fmac_f32_e32 v67, v49, v93
	ds_read_b128 v[90:93], v71 offset:13312
	s_waitcnt lgkmcnt(3)
	v_mul_f32_e32 v68, v47, v95
	v_pk_mul_f32 v[42:43], v[6:7], v[42:43]
	v_fmac_f32_e32 v68, v46, v94
	ds_read_b128 v[102:105], v71 offset:20480
	v_mul_f32_e32 v79, v43, v79
	v_fmac_f32_e32 v68, v48, v96
	v_fmac_f32_e32 v79, v42, v78
	s_waitcnt lgkmcnt(3)
	v_mul_f32_e32 v78, v43, v87
	v_fmac_f32_e32 v68, v49, v97
	ds_read_b128 v[94:97], v71 offset:17408
	s_waitcnt lgkmcnt(3)
	v_mul_f32_e32 v77, v47, v99
	v_pk_mul_f32 v[44:45], v[8:9], v[44:45]
	v_fmac_f32_e32 v78, v42, v86
	v_fmac_f32_e32 v77, v46, v98
	v_fmac_f32_e32 v78, v44, v88
	v_add_f32_e32 v67, 0, v67
	v_fmac_f32_e32 v77, v48, v100
	ds_read_b128 v[106:109], v71 offset:24576
	v_fmac_f32_e32 v78, v45, v89
	v_fmac_f32_e32 v77, v49, v101
	ds_read_b128 v[98:101], v71 offset:21504
	s_waitcnt lgkmcnt(3)
	v_mul_f32_e32 v103, v47, v103
	v_add_f32_e32 v67, v67, v78
	v_mul_f32_e32 v78, v43, v91
	v_fmac_f32_e32 v103, v46, v102
	v_fmac_f32_e32 v78, v42, v90
	v_fmac_f32_e32 v103, v48, v104
	v_fmac_f32_e32 v78, v44, v92
	v_add_f32_e32 v68, 0, v68
	v_fmac_f32_e32 v103, v49, v105
	ds_read_b128 v[110:113], v71 offset:28672
	v_fmac_f32_e32 v78, v45, v93
	v_add_f32_e32 v114, 0, v103
	ds_read_b128 v[102:105], v71 offset:25600
	s_waitcnt lgkmcnt(3)
	v_mul_f32_e32 v107, v47, v107
	v_add_f32_e32 v68, v68, v78
	v_mul_f32_e32 v78, v43, v95
	v_fmac_f32_e32 v107, v46, v106
	v_fmac_f32_e32 v78, v42, v94
	v_fmac_f32_e32 v107, v48, v108
	v_fmac_f32_e32 v78, v44, v96
	v_add_f32_e32 v77, 0, v77
	v_fmac_f32_e32 v107, v49, v109
	v_fmac_f32_e32 v78, v45, v97
	v_add_f32_e32 v115, 0, v107
	ds_read_b128 v[106:109], v71 offset:29696
	s_waitcnt lgkmcnt(2)
	v_mul_f32_e32 v111, v47, v111
	v_add_f32_e32 v77, v77, v78
	v_mul_f32_e32 v78, v43, v99
	v_fmac_f32_e32 v111, v46, v110
	v_fmac_f32_e32 v78, v42, v98
	v_fmac_f32_e32 v111, v48, v112
	v_fmac_f32_e32 v78, v44, v100
	v_fmac_f32_e32 v111, v49, v113
	v_fmac_f32_e32 v78, v45, v101
	v_add_f32_e32 v110, 0, v111
	v_add_f32_e32 v111, v114, v78
	s_waitcnt lgkmcnt(1)
	v_mul_f32_e32 v78, v43, v103
	v_fmac_f32_e32 v78, v42, v102
	v_fmac_f32_e32 v79, v44, v80
	v_fmac_f32_e32 v78, v44, v104
	v_add_f32_e32 v59, 0, v59
	v_fmac_f32_e32 v79, v45, v81
	v_fmac_f32_e32 v78, v45, v105
	v_mul_f32_e32 v83, v43, v83
	v_add_f32_e32 v59, v59, v79
	v_add_f32_e32 v114, v115, v78
	ds_read_b128 v[78:81], v71 offset:2048
	v_fmac_f32_e32 v83, v42, v82
	s_waitcnt lgkmcnt(1)
	v_mul_f32_e32 v82, v43, v107
	v_fmac_f32_e32 v82, v42, v106
	v_fmac_f32_e32 v83, v44, v84
	v_fmac_f32_e32 v82, v44, v108
	v_add_f32_e32 v57, 0, v57
	v_fmac_f32_e32 v83, v45, v85
	v_fmac_f32_e32 v82, v45, v109
	v_pk_mul_f32 v[38:39], v[10:11], v[38:39]
	v_add_f32_e32 v57, v57, v83
	v_add_f32_e32 v115, v110, v82
	ds_read_b128 v[82:85], v71 offset:3072
	s_waitcnt lgkmcnt(1)
	v_mul_f32_e32 v79, v39, v79
	v_pk_mul_f32 v[40:41], v[12:13], v[40:41]
	v_fmac_f32_e32 v79, v38, v78
	v_fmac_f32_e32 v79, v40, v80
	v_fmac_f32_e32 v79, v41, v81
	ds_read_b128 v[86:89], v71 offset:6144
	v_add_f32_e32 v57, v57, v79
	ds_read_b128 v[78:81], v71 offset:7168
	v_pk_mul_f32 v[34:35], v[14:15], v[34:35]
	v_add_f32_e32 v53, v53, v69
	s_waitcnt lgkmcnt(1)
	v_mul_f32_e32 v87, v39, v87
	v_and_b32_e32 v69, 64, v75
	s_waitcnt lgkmcnt(0)
; DI unsigned pk2(float a, float b) { f32x2 v = {a, b}; bf16x2v r = __builtin_convertvector(v, bf16x2v); return __builtin_bit_cast(unsigned, r); }
; DI void phase0(const Params& p, char* smem) {
;     ...
;         ss = wave_sum(ss);
;         const float rstd = 1.0f / sqrtf(ss * (1.0f / 1024.0f) + EPS);
; #pragma unroll
;         for (int i = 0; i < 4; ++i) {
;             const f32x4 xv = xg[i] * rstd;
;             *(u32x2*)(xr + i * 256 + lane * 4) = (u32x2){pk2(xv[0], xv[1]), pk2(xv[2], xv[3])};
;         }
;         const bool h5 = (lane & 32) != 0, h4 = (lane & 16) != 0, h3 = (lane & 8) != 0;
;         float a4[4], a2[2];
; #pragma unroll
;         for (int j = 0; j < 4; ++j) { const float keep = h5 ? fa[4 + j] : fa[j], send = h5 ? fa[j] : fa[4 + j]; a4[j] = keep + __shfl_xor(send, 32); }
; #pragma unroll
;         for (int j = 0; j < 2; ++j) { const float keep = h4 ? a4[2 + j] : a4[j], send = h4 ? a4[j] : a4[2 + j]; a2[j] = keep + __shfl_xor(send, 16); }
;         float c1;
;         { const float keep = h3 ? a2[1] : a2[0], send = h3 ? a2[0] : a2[1]; c1 = keep + __shfl_xor(send, 8); }
;         c1 += __shfl_xor(c1, 4); c1 += __shfl_xor(c1, 2); c1 += __shfl_xor(c1, 1);
	v_mul_f32_e32 v79, v35, v79
	v_fmac_f32_e32 v87, v38, v86
	v_fmac_f32_e32 v79, v34, v78
	v_add_u32_e32 v69, 64, v69
	v_xor_b32_e32 v78, 32, v75
	v_fmac_f32_e32 v87, v40, v88
	v_pk_mul_f32 v[36:37], v[16:17], v[36:37]
	v_cmp_lt_i32_e32 vcc, v78, v69
	v_fmac_f32_e32 v87, v41, v89
	v_fmac_f32_e32 v79, v36, v80
	v_cndmask_b32_e32 v78, v75, v78, vcc
	v_add_f32_e32 v59, v59, v87
	v_fmac_f32_e32 v79, v37, v81
	v_lshlrev_b32_e32 v78, 2, v78
	v_add_f32_e32 v59, v59, v79
	ds_bpermute_b32 v79, v78, v53
	ds_read_b128 v[90:93], v71 offset:10240
	ds_read_b128 v[86:89], v71 offset:11264
	ds_read_b128 v[94:97], v71 offset:14336
	v_mul_f32_e32 v83, v35, v83
	s_waitcnt lgkmcnt(3)
	v_add_f32_e32 v53, v53, v79
	v_xor_b32_e32 v79, 16, v75
	v_cmp_lt_i32_e32 vcc, v79, v69
	s_waitcnt lgkmcnt(2)
	v_mul_f32_e32 v91, v39, v91
	v_fmac_f32_e32 v91, v38, v90
	v_cndmask_b32_e32 v79, v75, v79, vcc
	v_lshlrev_b32_e32 v79, 2, v79
	v_fmac_f32_e32 v91, v40, v92
	ds_bpermute_b32 v81, v79, v53
	v_fmac_f32_e32 v91, v41, v93
	v_add_f32_e32 v67, v67, v91
	ds_read_b128 v[90:93], v71 offset:15360
	s_waitcnt lgkmcnt(3)
	v_mul_f32_e32 v80, v35, v87
	v_fmac_f32_e32 v80, v34, v86
	v_fmac_f32_e32 v80, v36, v88
	s_waitcnt lgkmcnt(1)
	v_add_f32_e32 v53, v53, v81
	v_xor_b32_e32 v81, 8, v75
	v_mul_f32_e32 v95, v39, v95
	v_fmac_f32_e32 v80, v37, v89
	v_cmp_lt_i32_e32 vcc, v81, v69
	v_fmac_f32_e32 v95, v38, v94
	v_add_f32_e32 v80, v67, v80
	s_waitcnt lgkmcnt(0)
	v_mul_f32_e32 v67, v35, v91
	v_cndmask_b32_e32 v81, v75, v81, vcc
	ds_read_b128 v[98:101], v71 offset:18432
	v_fmac_f32_e32 v95, v40, v96
	v_fmac_f32_e32 v83, v34, v82
	v_fmac_f32_e32 v67, v34, v90
	v_lshlrev_b32_e32 v81, 2, v81
	v_fmac_f32_e32 v95, v41, v97
	v_fmac_f32_e32 v83, v36, v84
	v_fmac_f32_e32 v67, v36, v92
	ds_bpermute_b32 v82, v81, v53
	v_add_f32_e32 v68, v68, v95
	v_fmac_f32_e32 v83, v37, v85
	v_fmac_f32_e32 v67, v37, v93
	v_add_f32_e32 v57, v57, v83
	v_add_f32_e32 v83, v68, v67
	v_xor_b32_e32 v68, 4, v75
	v_cmp_lt_i32_e32 vcc, v68, v69
	ds_read_b128 v[94:97], v71 offset:19456
	s_waitcnt lgkmcnt(2)
	v_mul_f32_e32 v99, v39, v99
	v_cndmask_b32_e32 v68, v75, v68, vcc
	v_fmac_f32_e32 v99, v38, v98
	s_waitcnt lgkmcnt(1)
	v_add_f32_e32 v53, v53, v82
	v_lshlrev_b32_e32 v82, 2, v68
	v_fmac_f32_e32 v99, v40, v100
	ds_bpermute_b32 v68, v82, v53
	ds_read_b128 v[102:105], v71 offset:22528
	v_fmac_f32_e32 v99, v41, v101
	v_add_f32_e32 v77, v77, v99
	ds_read_b128 v[98:101], v71 offset:23552
	s_waitcnt lgkmcnt(3)
	v_mul_f32_e32 v67, v35, v95
	v_fmac_f32_e32 v67, v34, v94
	v_fmac_f32_e32 v67, v36, v96
	s_waitcnt lgkmcnt(2)
	v_add_f32_e32 v53, v53, v68
	v_xor_b32_e32 v68, 2, v75
	s_waitcnt lgkmcnt(1)
	v_mul_f32_e32 v103, v39, v103
	v_fmac_f32_e32 v67, v37, v97
	v_cmp_lt_i32_e32 vcc, v68, v69
	v_fmac_f32_e32 v103, v38, v102
	v_add_f32_e32 v77, v77, v67
	s_waitcnt lgkmcnt(0)
	v_mul_f32_e32 v67, v35, v99
	v_cndmask_b32_e32 v68, v75, v68, vcc
	v_fmac_f32_e32 v103, v40, v104
	v_lshlrev_b32_e32 v84, 2, v68
	v_fmac_f32_e32 v67, v34, v98
	v_fmac_f32_e32 v103, v41, v105
	ds_bpermute_b32 v68, v84, v53
	v_fmac_f32_e32 v67, v36, v100
	v_add_f32_e32 v116, v111, v103
	v_fmac_f32_e32 v67, v37, v101
	v_add_f32_e32 v85, v116, v67
	v_xor_b32_e32 v67, 1, v75
	v_cmp_lt_i32_e32 vcc, v67, v69
	s_waitcnt lgkmcnt(0)
	v_add_f32_e32 v53, v53, v68
	ds_read_b128 v[106:109], v71 offset:26624
	ds_read_b128 v[102:105], v71 offset:27648
	v_cndmask_b32_e32 v67, v75, v67, vcc
	v_lshlrev_b32_e32 v69, 2, v67
	ds_bpermute_b32 v67, v69, v53
	s_waitcnt lgkmcnt(2)
	v_mul_f32_e32 v107, v39, v107
	v_fmac_f32_e32 v107, v38, v106
	v_fmac_f32_e32 v107, v40, v108
	ds_read_b128 v[110:113], v71 offset:30720
	s_waitcnt lgkmcnt(1)
	v_add_f32_e32 v53, v53, v67
	v_fmamk_f32 v53, v53, 0x3a800000, v72
	v_mul_f32_e32 v67, 0x4f800000, v53
	v_cmp_gt_f32_e32 vcc, s43, v53
	v_fmac_f32_e32 v107, v41, v109
	v_add_f32_e32 v114, v114, v107
	v_cndmask_b32_e32 v53, v53, v67, vcc
	v_sqrt_f32_e32 v67, v53
	ds_read_b128 v[106:109], v71 offset:31744
	v_mul_f32_e32 v68, v35, v103
	v_fmac_f32_e32 v68, v34, v102
	v_add_u32_e32 v87, -1, v67
	v_fma_f32 v88, -v87, v67, v53
	v_cmp_ge_f32_e64 s[16:17], 0, v88
	v_add_u32_e32 v88, 1, v67
	v_fmac_f32_e32 v68, v36, v104
	v_cndmask_b32_e64 v87, v67, v87, s[16:17]
	v_fma_f32 v67, -v88, v67, v53
	v_cmp_lt_f32_e64 s[16:17], 0, v67
	s_waitcnt lgkmcnt(1)
	v_mul_f32_e32 v111, v39, v111
	v_fmac_f32_e32 v68, v37, v105
	v_cndmask_b32_e64 v67, v87, v88, s[16:17]
	v_mul_f32_e32 v87, 0x37800000, v67
	v_cndmask_b32_e32 v67, v67, v87, vcc
	v_cmp_class_f32_e32 vcc, v53, v73
	v_fmac_f32_e32 v111, v38, v110
	v_add_f32_e32 v86, v114, v68
	v_cndmask_b32_e32 v53, v67, v53, vcc
	v_div_scale_f32 v67, s[16:17], v53, v53, 1.0
	s_waitcnt lgkmcnt(0)
	v_mul_f32_e32 v68, v35, v107
	v_rcp_f32_e32 v87, v67
	v_fmac_f32_e32 v111, v40, v112
	v_fmac_f32_e32 v68, v34, v106
	v_fmac_f32_e32 v111, v41, v113
	v_fmac_f32_e32 v68, v36, v108
	v_add_f32_e32 v110, v115, v111
	v_fmac_f32_e32 v68, v37, v109
	v_add_f32_e32 v88, v110, v68
	v_fma_f32 v68, -v67, v87, 1.0
	v_fmac_f32_e32 v87, v68, v87
	v_div_scale_f32 v68, vcc, 1.0, v53, 1.0
	v_mul_f32_e32 v89, v68, v87
	v_fma_f32 v90, -v67, v89, v68
	v_fmac_f32_e32 v89, v90, v87
	v_fma_f32 v67, -v67, v89, v68
	v_div_fmas_f32 v67, v67, v87, v89
	v_div_fixup_f32 v68, v67, v53, 1.0
	v_cndmask_b32_e64 v53, v57, v77, s[4:5]
	ds_bpermute_b32 v53, v78, v53
	v_pk_mul_f32 v[48:49], v[48:49], v[68:69] op_sel_hi:[1,0]
	v_pk_mul_f32 v[46:47], v[46:47], v[68:69] op_sel_hi:[1,0]
	v_mov_b32_e32 v67, v55
	v_cvt_pk_bf16_f32 v46, v46, v47
	v_cvt_pk_bf16_f32 v47, v48, v49
	v_cndmask_b32_e64 v48, v77, v57, s[4:5]
	s_waitcnt lgkmcnt(0)
; DI unsigned pk2(float a, float b) { f32x2 v = {a, b}; bf16x2v r = __builtin_convertvector(v, bf16x2v); return __builtin_bit_cast(unsigned, r); }
; DI void phase0(const Params& p, char* smem) {
;     ...
;         const float rstd = 1.0f / sqrtf(ss * (1.0f / 1024.0f) + EPS);
; #pragma unroll
;         for (int i = 0; i < 4; ++i) {
;             const f32x4 xv = xg[i] * rstd;
;             *(u32x2*)(xr + i * 256 + lane * 4) = (u32x2){pk2(xv[0], xv[1]), pk2(xv[2], xv[3])};
;         }
;         const bool h5 = (lane & 32) != 0, h4 = (lane & 16) != 0, h3 = (lane & 8) != 0;
;         float a4[4], a2[2];
; #pragma unroll
;         for (int j = 0; j < 4; ++j) { const float keep = h5 ? fa[4 + j] : fa[j], send = h5 ? fa[j] : fa[4 + j]; a4[j] = keep + __shfl_xor(send, 32); }
; #pragma unroll
;         for (int j = 0; j < 2; ++j) { const float keep = h4 ? a4[2 + j] : a4[j], send = h4 ? a4[j] : a4[2 + j]; a2[j] = keep + __shfl_xor(send, 16); }
;         float c1;
;         { const float keep = h3 ? a2[1] : a2[0], send = h3 ? a2[0] : a2[1]; c1 = keep + __shfl_xor(send, 8); }
;         c1 += __shfl_xor(c1, 4); c1 += __shfl_xor(c1, 2); c1 += __shfl_xor(c1, 1);
;         if ((lane & 7) == 0) {
;             const float z = c1 * rstd + bfv;
;             lf_out[lane >> 3] = fminf(z, 0.f) - log1pf(expf(-fabsf(z)));
	v_add_f32_e32 v48, v48, v53
	v_cndmask_b32_e64 v53, v59, v85, s[4:5]
	ds_bpermute_b32 v53, v78, v53
	v_cndmask_b32_e64 v57, v80, v86, s[4:5]
	v_cndmask_b32_e64 v49, v85, v59, s[4:5]
	ds_bpermute_b32 v57, v78, v57
	v_cndmask_b32_e64 v59, v83, v88, s[4:5]
	ds_bpermute_b32 v59, v78, v59
	s_waitcnt lgkmcnt(2)
	v_add_f32_e32 v49, v49, v53
	v_cndmask_b32_e64 v53, v86, v80, s[4:5]
	s_waitcnt lgkmcnt(1)
	v_add_f32_e32 v53, v53, v57
	v_cndmask_b32_e64 v57, v88, v83, s[4:5]
	s_waitcnt lgkmcnt(0)
	v_add_f32_e32 v57, v57, v59
	v_lshl_add_u64 v[64:65], v[64:65], 0, v[66:67]
	v_cndmask_b32_e64 v59, v48, v53, s[6:7]
	v_cndmask_b32_e64 v66, v49, v57, s[6:7]
	ds_bpermute_b32 v59, v79, v59
	ds_bpermute_b32 v66, v79, v66
	global_store_dwordx2 v[64:65], v[46:47], off sc0 sc1
	v_cndmask_b32_e64 v46, v53, v48, s[6:7]
	v_cndmask_b32_e64 v47, v57, v49, s[6:7]
	s_waitcnt lgkmcnt(1)
	v_add_f32_e32 v46, v46, v59
	s_waitcnt lgkmcnt(0)
	v_add_f32_e32 v47, v47, v66
	v_cndmask_b32_e64 v48, v46, v47, s[8:9]
	ds_bpermute_b32 v48, v81, v48
	v_pk_mul_f32 v[42:43], v[42:43], v[68:69] op_sel_hi:[1,0]
	v_pk_mul_f32 v[44:45], v[44:45], v[68:69] op_sel_hi:[1,0]
	v_cvt_pk_bf16_f32 v42, v42, v43
	v_cndmask_b32_e64 v43, v47, v46, s[8:9]
	s_waitcnt lgkmcnt(0)
	v_add_f32_e32 v46, v43, v48
	ds_bpermute_b32 v47, v82, v46
	v_cvt_pk_bf16_f32 v43, v44, v45
	global_store_dwordx2 v[64:65], v[42:43], off offset:512 sc0 sc1
	v_pk_mul_f32 v[40:41], v[40:41], v[68:69] op_sel_hi:[1,0]
	v_pk_mul_f32 v[38:39], v[38:39], v[68:69] op_sel_hi:[1,0]
	s_waitcnt lgkmcnt(0)
	v_add_f32_e32 v42, v46, v47
	ds_bpermute_b32 v43, v84, v42
	v_cvt_pk_bf16_f32 v38, v38, v39
	v_cvt_pk_bf16_f32 v39, v40, v41
	global_store_dwordx2 v[64:65], v[38:39], off offset:1024 sc0 sc1
	v_pk_mul_f32 v[38:39], v[36:37], v[68:69] op_sel_hi:[1,0]
	s_waitcnt lgkmcnt(0)
	v_add_f32_e32 v36, v42, v43
	ds_bpermute_b32 v37, v69, v36
	v_pk_mul_f32 v[34:35], v[34:35], v[68:69] op_sel_hi:[1,0]
	s_nop 0
	v_cvt_pk_bf16_f32 v34, v34, v35
	v_cvt_pk_bf16_f32 v35, v38, v39
	global_store_dwordx2 v[64:65], v[34:35], off offset:1536 sc0 sc1
	s_and_saveexec_b64 s[16:17], s[10:11]
	s_cbranch_execz .LBB0_55
	s_waitcnt lgkmcnt(0)
	v_add_f32_e32 v36, v36, v37
	v_fma_f32 v38, v68, v36, v1
	v_mul_f32_e64 v36, |v38|, s44
	v_fma_f32 v37, |v38|, s44, -v36
	v_rndne_f32_e32 v39, v36
	v_fma_f32 v37, |v38|, s45, v37
	v_sub_f32_e32 v36, v36, v39
	v_add_f32_e32 v36, v36, v37
	v_exp_f32_e32 v40, v36
	v_cvt_i32_f32_e32 v39, v39
	v_lshl_add_u64 v[34:35], s[54:55], 0, v[62:63]
	v_lshlrev_b64 v[36:37], 5, v[60:61]
	v_lshl_add_u64 v[34:35], v[34:35], 0, v[36:37]
	v_ldexp_f32 v36, v40, v39
	v_cmp_ngt_f32_e64 vcc, |v38|, s46
	v_min_f32_e32 v53, 0, v38
	s_nop 0
	v_cndmask_b32_e32 v36, 0, v36, vcc
	v_cmp_nlt_f32_e64 vcc, |v38|, s47
	s_nop 1
	v_cndmask_b32_e32 v59, v76, v36, vcc
	v_add_f32_e32 v38, 1.0, v59
	v_add_f32_e32 v36, -1.0, v38
	v_sub_f32_e32 v37, v36, v38
	v_add_f32_e32 v37, 1.0, v37
	v_sub_f32_e32 v36, v59, v36
	v_add_f32_e32 v39, v36, v37
	v_frexp_mant_f32_e32 v40, v38
	v_cvt_f64_f32_e32 v[36:37], v38
	v_frexp_exp_i32_f64_e32 v36, v[36:37]
	v_cmp_gt_f32_e32 vcc, s49, v40
	s_nop 1
	v_subbrev_co_u32_e32 v44, vcc, 0, v36, vcc
	v_sub_u32_e32 v36, 0, v44
	v_ldexp_f32 v37, v38, v36
	v_add_f32_e32 v38, -1.0, v37
	v_add_f32_e32 v40, 1.0, v37
	v_ldexp_f32 v36, v39, v36
	v_add_f32_e32 v39, 1.0, v38
	v_add_f32_e32 v41, -1.0, v40
	v_sub_f32_e32 v39, v37, v39
	v_sub_f32_e32 v37, v37, v41
	v_add_f32_e32 v39, v36, v39
	v_add_f32_e32 v36, v36, v37
	v_add_f32_e32 v45, v40, v36
	v_rcp_f32_e32 v47, v45
	v_sub_f32_e32 v37, v40, v45
	v_add_f32_e32 v46, v36, v37
	v_add_f32_e32 v37, v38, v39
	v_mul_f32_e32 v49, v37, v47
	v_sub_f32_e32 v36, v38, v37
	v_mul_f32_e32 v38, v45, v49
	v_fma_f32 v40, v49, v45, -v38
	v_fmac_f32_e32 v40, v49, v46
	v_add_f32_e32 v48, v39, v36
	v_add_f32_e32 v36, v38, v40
	v_sub_f32_e32 v39, v37, v36
	v_pk_add_f32 v[42:43], v[36:37], v[38:39] neg_lo:[0,1] neg_hi:[0,1]
	v_mov_b32_e32 v41, v36
	v_pk_add_f32 v[36:37], v[42:43], v[40:41] neg_lo:[0,1] neg_hi:[0,1]
	v_cmp_neq_f32_e32 vcc, s48, v59
	v_add_f32_e32 v37, v48, v37
	v_add_f32_e32 v36, v36, v37
	v_add_f32_e32 v37, v39, v36
	v_mul_f32_e32 v48, v47, v37
	v_mul_f32_e32 v38, v45, v48
	v_fma_f32 v40, v48, v45, -v38
	v_fmac_f32_e32 v40, v48, v46
	v_sub_f32_e32 v39, v39, v37
	v_add_f32_e32 v45, v36, v39
	v_add_f32_e32 v36, v38, v40
	v_sub_f32_e32 v39, v37, v36
	v_pk_add_f32 v[42:43], v[36:37], v[38:39] neg_lo:[0,1] neg_hi:[0,1]
	v_mov_b32_e32 v41, v36
	v_pk_add_f32 v[36:37], v[42:43], v[40:41] neg_lo:[0,1] neg_hi:[0,1]
	s_nop 0
	v_add_f32_e32 v37, v45, v37
	v_add_f32_e32 v36, v36, v37
	v_add_f32_e32 v37, v49, v48
	v_add_f32_e32 v36, v39, v36
	v_sub_f32_e32 v38, v37, v49
	v_mul_f32_e32 v36, v47, v36
	v_sub_f32_e32 v38, v48, v38
	v_add_f32_e32 v38, v38, v36
	v_add_f32_e32 v40, v37, v38
	v_mul_f32_e32 v41, v40, v40
	v_fmamk_f32 v36, v41, 0x3e9b6dac, v74
	v_fmaak_f32 v57, v41, v36, 0x3f2aaada
	v_cvt_f32_i32_e32 v36, v44
	v_sub_f32_e32 v37, v40, v37
	v_sub_f32_e32 v37, v38, v37
	v_ldexp_f32 v42, v37, 1
	v_mul_f32_e32 v37, v40, v41
	v_ldexp_f32 v39, v40, 1
	v_pk_mul_f32 v[40:41], v[36:37], v[56:57]
	s_nop 0
	v_fma_f32 v38, v36, s50, -v40
	v_fmac_f32_e32 v38, 0xb102e308, v36
	v_pk_add_f32 v[36:37], v[40:41], v[38:39]
	s_nop 0
	v_sub_f32_e32 v39, v37, v39
	v_sub_f32_e32 v39, v41, v39
	v_add_f32_e32 v43, v42, v39
	v_mov_b32_e32 v42, v40
	v_pk_add_f32 v[40:41], v[36:37], v[40:41] neg_lo:[0,1] neg_hi:[0,1]
	v_pk_add_f32 v[44:45], v[36:37], v[42:43]
	v_mov_b32_e32 v39, v36
	v_mov_b32_e32 v41, v45
	v_pk_add_f32 v[46:47], v[38:39], v[40:41] neg_lo:[0,1] neg_hi:[0,1]
	v_pk_add_f32 v[38:39], v[38:39], v[40:41]
	v_mov_b32_e32 v42, v43
	v_pk_add_f32 v[40:41], v[38:39], v[36:37] op_sel:[1,0] op_sel_hi:[0,1] neg_lo:[0,1] neg_hi:[0,1]
	v_pk_add_f32 v[48:49], v[44:45], v[40:41] op_sel_hi:[1,0] neg_lo:[0,1] neg_hi:[0,1]
	v_mov_b32_e32 v44, v45
	v_mov_b32_e32 v45, v39
	v_pk_mov_b32 v[40:41], v[36:37], v[40:41] op_sel:[1,0]
	v_mov_b32_e32 v43, v36
	v_pk_add_f32 v[40:41], v[44:45], v[40:41] neg_lo:[0,1] neg_hi:[0,1]
	v_mov_b32_e32 v48, v46
	v_pk_add_f32 v[36:37], v[42:43], v[40:41] neg_lo:[0,1] neg_hi:[0,1]
	v_mov_b32_e32 v47, v39
	v_pk_add_f32 v[40:41], v[48:49], v[36:37]
	s_nop 0
	v_pk_add_f32 v[42:43], v[40:41], v[40:41] op_sel:[0,1] op_sel_hi:[1,0]
	s_nop 0
	v_pk_add_f32 v[38:39], v[38:39], v[42:43] op_sel:[1,0] op_sel_hi:[0,1]
	v_mov_b32_e32 v41, v38
	v_pk_add_f32 v[44:45], v[40:41], v[46:47] neg_lo:[0,1] neg_hi:[0,1]
	v_mov_b32_e32 v37, v42
	v_sub_f32_e32 v39, v40, v44
	v_pk_add_f32 v[36:37], v[36:37], v[44:45] neg_lo:[0,1] neg_hi:[0,1]
	v_sub_f32_e32 v39, v46, v39
	v_add_f32_e32 v36, v36, v39
	v_add_f32_e32 v36, v36, v37
	v_add_f32_e32 v36, v38, v36
	v_cndmask_b32_e32 v36, v76, v36, vcc
	v_cmp_lt_f32_e64 vcc, |v59|, s51
	s_nop 1
	v_cndmask_b32_e32 v36, v36, v59, vcc
	v_sub_f32_e32 v36, v53, v36
	v_mov_b32_e32 v53, v55
	v_lshl_add_u64 v[34:35], v[34:35], 0, v[52:53]
	global_store_dword v[34:35], v36, off sc0 sc1

; DI void phase0(const Params& p, char* smem) {
;     ...
;         if (!src) {
; #pragma unroll
;             for (int i = 0; i < 4; ++i) *(u32x2*)(xr + i * 256 + lane * 4) = (u32x2){0u, 0u};
;             continue;
;         }
.LBB0_56:
	s_andn2_saveexec_b64 s[16:17], s[28:29]
	s_cbranch_execz .LBB0_25
	v_mov_b32_e32 v67, v55
	s_mov_b32 s25, s24
	s_waitcnt vmcnt(7)
	v_lshl_add_u64 v[34:35], v[64:65], 0, v[66:67]
	s_waitcnt lgkmcnt(0)
	v_mov_b64_e32 v[36:37], s[24:25]
	global_store_dwordx2 v[34:35], v[36:37], off sc0 sc1
	global_store_dwordx2 v[34:35], v[36:37], off offset:512 sc0 sc1
	global_store_dwordx2 v[34:35], v[36:37], off offset:1024 sc0 sc1
	global_store_dwordx2 v[34:35], v[36:37], off offset:1536 sc0 sc1
	s_branch .LBB0_25

; DI void phase0(const Params& p, char* smem) {
;     ...
;     for (int i = blockIdx.x * NT + tid; i < NR; i += gridDim.x * NT) p.rowss[i] = 0.f;
;     if (blockIdx.x == 0 && tid < 128) p.ctrl[tid] = 0u;
.LBB0_60:
	v_ashrrev_i32_e32 v3, 31, v2
	v_lshl_add_u64 v[4:5], v[2:3], 2, s[60:61]
	v_add_u32_e32 v2, s8, v2
	v_cmp_lt_i32_e32 vcc, s9, v2
	s_or_b64 s[6:7], vcc, s[6:7]
	global_store_dword v[4:5], v1, off sc0 sc1
	s_andn2_b64 exec, exec, s[6:7]
	s_cbranch_execnz .LBB0_60
.LBB0_61:
	s_or_b64 exec, exec, s[4:5]
	s_cmp_eq_u32 s2, 0
	s_movk_i32 s6, 0x80
	s_cselect_b64 s[4:5], -1, 0
	v_cmp_gt_i32_e32 vcc, s6, v50
	s_and_b64 s[6:7], s[4:5], vcc
	s_and_saveexec_b64 s[4:5], s[6:7]
	s_cbranch_execz .LBB0_63
	v_lshl_add_u64 v[2:3], v[50:51], 2, s[56:57]
	v_mov_b32_e32 v1, 0
	global_store_dword v[2:3], v1, off sc0 sc1

; DI unsigned xb_add(unsigned* p, unsigned v) { return __hip_atomic_fetch_add(p, v, __ATOMIC_RELAXED, __HIP_MEMORY_SCOPE_AGENT); }
; DI void xcd_barrier(const XcdBarrier& b) {
;     ...
;         const unsigned old = xb_add(&bar[XB_XSUB(b.x)], 1u);
;         const unsigned gen = old / nloc;
;         if (old + 1u == (gen + 1u) * nloc) {
;             __builtin_amdgcn_fence(__ATOMIC_RELEASE, "agent");
;             asm volatile("s_waitcnt vmcnt(0)" ::: "memory");
;             const unsigned og = xb_add(&bar[XB_TOP], 1u);
;             const unsigned tg = og / nx;
;             if (og + 1u == (tg + 1u) * nx) xb_add(&bar[XB_TOPGEN], 1u);
.LBB0_95:
	s_andn2_saveexec_b64 s[8:9], s[8:9]
	s_cbranch_execz .LBB0_115
	s_mov_b64 s[8:9], exec
	s_nop 0
	s_waitcnt lgkmcnt(0)
	s_waitcnt vmcnt(0)
	v_mbcnt_lo_u32_b32 v2, s8, 0
	v_mbcnt_hi_u32_b32 v2, s9, v2
	v_cmp_eq_u32_e32 vcc, 0, v2
	s_and_saveexec_b64 s[10:11], vcc
	s_cbranch_execz .LBB0_98
	s_bcnt1_i32_b64 s8, s[8:9]
	v_mov_b32_e32 v3, 0x3000
	v_mov_b32_e32 v4, s8
	global_atomic_add v3, v3, v4, s[58:59] offset:1024 sc0
